# v44 + EpiUp: leading half's ALIGN barrier moved after the i32->f32 block (its address math, loads and conversions run beside the trailing half's last MFMA block)
# baseline (speedup 1.0000x reference)
; #define PG8_STAGE(bufoff, gbase, voff) do { _Pragma("unroll") for (int _i = 0; _i < 2; ++_i) glds16_s((gbase), (voff)[_i], ldsb + (unsigned)((bufoff) + _i * 8192)); } while (0)
; #define PG8_LDA(dst, b, h) do { _Pragma("unroll") for (int m = 0; m < 4; ++m) _Pragma("unroll") for (int k = 0; k < 2; ++k) dst[m][k] = *(const LAS h16x8*)(lds + PG8_SA(b, h) + aoff + m * 2048 + k * 1024); } while (0)
; #define PG8_LDB(dst, b, h) do { _Pragma("unroll") for (int n = 0; n < 2; ++n) _Pragma("unroll") for (int k = 0; k < 2; ++k) dst[n][k] = *(const LAS h16x8*)(lds + PG8_SB(b, h) + boff + n * 2048 + k * 1024); } while (0)
; #define PG8_MMA(ai, bj, At, Bt) do { __builtin_amdgcn_s_setprio(1); _Pragma("unroll") for (int m = 0; m < 4; ++m) _Pragma("unroll") for (int n = 0; n < 2; ++n) _Pragma("unroll") for (int k = 0; k < 2; ++k) \
;         acc[ai][bj][m][n] = mma_step<I8>(Bt[n][k], At[m][k], acc[ai][bj][m][n]); __builtin_amdgcn_s_setprio(0); } while (0)
; #define PG8_WAIT_V(n) asm volatile("s_waitcnt vmcnt(" #n ")" ::: "memory")
; #define PG8_WAIT_L(n) asm volatile("s_waitcnt lgkmcnt(" #n ")" ::: "memory")
; #define PG8_BAR __builtin_amdgcn_s_barrier()
; template <class Prob, class Epi, bool I8 = false, bool ALIGN_EPI = true, bool SP2 = true>
; __device__ __forceinline__ void gemm_phase(LAS unsigned char* lds, int wave, const Prob& P, const Epi& E) {
;     ...
;             PG8_LDB(B0, 0, 0); PG8_LDB(B1, 0, 1); PG8_SCHED; PG8_LDA(At, 0, 0); PG8_STAGE(PG8_SA(1, 1), a1 + hstepA, voffA);
;             PG8_WAIT_V(8); PG8_WAIT_L(0); PG8_BAR; PG8_MMA(0, 0, At, B0); PG8_MMA(0, 1, At, B1); PG8_BAR; PG8_SCHED;
;             PG8_LDA(At, 0, 1); PG8_STAGE(PG8_SB(0, 0), b2, voffB); PG8_STAGE(PG8_SB(0, 1), b2 + hstepB, voffB); PG8_STAGE(PG8_SA(0, 0), a2, voffA);
;             PG8_WAIT_V(8); PG8_WAIT_L(0); PG8_BAR; PG8_MMA(1, 0, At, B0); PG8_MMA(1, 1, At, B1); PG8_BAR; PG8_SCHED;
;             PG8_LDB(B0, 1, 0); PG8_LDB(B1, 1, 1); PG8_SCHED; PG8_LDA(At, 1, 0); PG8_STAGE(PG8_SA(0, 1), a2 + hstepA, voffA);
;             PG8_WAIT_V(8); PG8_WAIT_L(0); PG8_BAR; PG8_MMA(0, 0, At, B0); PG8_MMA(0, 1, At, B1); PG8_BAR; PG8_SCHED;
;             PG8_LDA(At, 1, 1); PG8_STAGE(PG8_SB(1, 0), b3, voffB); PG8_STAGE(PG8_SB(1, 1), b3 + hstepB, voffB); PG8_STAGE(PG8_SA(1, 0), a3, voffA);
;             PG8_WAIT_V(8); PG8_WAIT_L(0); PG8_BAR; PG8_MMA(1, 0, At, B0); PG8_MMA(1, 1, At, B1); PG8_BAR; PG8_SCHED;
.LBB0_1065:
	v_add_u32_e32 v124, 0x10000, v210
	v_add_u32_e32 v140, 0x14000, v210
	ds_read_b128 v[104:107], v124
	ds_read_b128 v[112:115], v124 offset:1024
	ds_read_b128 v[120:123], v124 offset:2048
	ds_read_b128 v[124:127], v124 offset:3072
	ds_read_b128 v[128:131], v140
	ds_read_b128 v[132:135], v140 offset:1024
	ds_read_b128 v[136:139], v140 offset:2048
	ds_read_b128 v[140:143], v140 offset:3072
	s_cmp_eq_u32 s4, 12
	s_cselect_b32 s62, s96, vcc_lo
	s_cselect_b32 s63, s51, vcc_hi
	s_cselect_b32 s68, s97, s0
	s_cselect_b32 s69, s49, s1
	s_add_u32 s60, s62, 0x80
	s_addc_u32 s61, s63, 0
	ds_read_b128 v[144:147], v211
	ds_read_b128 v[164:167], v211 offset:1024
	ds_read_b128 v[168:171], v211 offset:2048
	ds_read_b128 v[172:175], v211 offset:3072
	ds_read_b128 v[176:179], v211 offset:4096
	ds_read_b128 v[180:183], v211 offset:5120
	ds_read_b128 v[184:187], v211 offset:6144
	ds_read_b128 v[188:191], v211 offset:7168
	s_mov_b32 s5, m0
	s_mov_b32 m0, s90
	s_nop 0
	global_load_lds_dwordx4 v250, s[44:45]
	s_mov_b32 m0, s5
	s_nop 0
	s_mov_b32 s5, m0
	s_mov_b32 m0, s92
	s_nop 0
	global_load_lds_dwordx4 v247, s[44:45]
	s_mov_b32 m0, s5
	s_waitcnt vmcnt(8)
	s_waitcnt lgkmcnt(0)
	s_barrier
	s_setprio 1
	s_waitcnt lgkmcnt(7)
	v_mfma_i32_16x16x64_i8 v[160:163], v[104:107], v[144:147], v[160:163]
	v_mfma_i32_16x16x64_i8 v[152:155], v[120:123], v[144:147], v[152:155]
	s_waitcnt lgkmcnt(5)
	v_mfma_i32_16x16x64_i8 v[52:55], v[104:107], v[168:171], v[52:55]
	v_mfma_i32_16x16x64_i8 v[80:83], v[120:123], v[168:171], v[80:83]
	s_waitcnt lgkmcnt(3)
	v_mfma_i32_16x16x64_i8 v[48:51], v[104:107], v[176:179], v[48:51]
	v_mfma_i32_16x16x64_i8 v[72:75], v[120:123], v[176:179], v[72:75]
	s_waitcnt lgkmcnt(1)
	v_mfma_i32_16x16x64_i8 v[44:47], v[104:107], v[184:187], v[44:47]
	v_mfma_i32_16x16x64_i8 v[68:71], v[120:123], v[184:187], v[68:71]
	v_mfma_i32_16x16x64_i8 v[160:163], v[112:115], v[164:167], v[160:163]
	v_mfma_i32_16x16x64_i8 v[152:155], v[124:127], v[164:167], v[152:155]
	v_mfma_i32_16x16x64_i8 v[52:55], v[112:115], v[172:175], v[52:55]
	v_mfma_i32_16x16x64_i8 v[80:83], v[124:127], v[172:175], v[80:83]
	v_mfma_i32_16x16x64_i8 v[48:51], v[112:115], v[180:183], v[48:51]
	v_mfma_i32_16x16x64_i8 v[72:75], v[124:127], v[180:183], v[72:75]
	s_waitcnt lgkmcnt(0)
	v_mfma_i32_16x16x64_i8 v[44:47], v[112:115], v[188:191], v[44:47]
	v_mfma_i32_16x16x64_i8 v[68:71], v[124:127], v[188:191], v[68:71]
	s_setprio 0
	s_setprio 1
	v_mfma_i32_16x16x64_i8 v[116:119], v[128:131], v[144:147], v[116:119]
	v_mfma_i32_16x16x64_i8 v[28:31], v[136:139], v[144:147], v[28:31]
	v_mfma_i32_16x16x64_i8 v[100:103], v[128:131], v[168:171], v[100:103]
	v_mfma_i32_16x16x64_i8 v[24:27], v[136:139], v[168:171], v[24:27]
	v_mfma_i32_16x16x64_i8 v[96:99], v[128:131], v[176:179], v[96:99]
	v_mfma_i32_16x16x64_i8 v[20:23], v[136:139], v[176:179], v[20:23]
	v_mfma_i32_16x16x64_i8 v[92:95], v[128:131], v[184:187], v[92:95]
	v_mfma_i32_16x16x64_i8 v[16:19], v[136:139], v[184:187], v[16:19]
	v_mfma_i32_16x16x64_i8 v[116:119], v[132:135], v[164:167], v[116:119]
	v_mfma_i32_16x16x64_i8 v[28:31], v[140:143], v[164:167], v[28:31]
	v_mfma_i32_16x16x64_i8 v[100:103], v[132:135], v[172:175], v[100:103]
	v_mfma_i32_16x16x64_i8 v[24:27], v[140:143], v[172:175], v[24:27]
	v_mfma_i32_16x16x64_i8 v[96:99], v[132:135], v[180:183], v[96:99]
	v_mfma_i32_16x16x64_i8 v[20:23], v[140:143], v[180:183], v[20:23]
	v_mfma_i32_16x16x64_i8 v[92:95], v[132:135], v[188:191], v[92:95]
	v_mfma_i32_16x16x64_i8 v[16:19], v[140:143], v[188:191], v[16:19]
	s_setprio 0
	s_barrier
	ds_read_b128 v[144:147], v211 offset:16384
	ds_read_b128 v[164:167], v211 offset:17408
	ds_read_b128 v[168:171], v211 offset:18432
	ds_read_b128 v[172:175], v211 offset:19456
	ds_read_b128 v[176:179], v211 offset:20480
	ds_read_b128 v[180:183], v211 offset:21504
	ds_read_b128 v[184:187], v211 offset:22528
	ds_read_b128 v[188:191], v211 offset:23552
	s_mov_b32 s5, m0
	s_mov_b32 m0, s73
	s_nop 0
	global_load_lds_dwordx4 v217, s[68:69]
	s_mov_b32 m0, s5
	s_add_u32 s6, s68, 0x40000
	s_mov_b32 s5, m0
	s_mov_b32 m0, s74
	s_nop 0
	global_load_lds_dwordx4 v248, s[68:69]
	s_mov_b32 m0, s5
	s_addc_u32 s7, s69, 0
	s_mov_b32 s5, m0
	s_mov_b32 m0, s75
	s_nop 0
	global_load_lds_dwordx4 v217, s[6:7]
	s_mov_b32 m0, s5
	s_nop 0
	s_mov_b32 s5, m0
	s_mov_b32 m0, s80
	s_nop 0
	global_load_lds_dwordx4 v248, s[6:7]
	s_mov_b32 m0, s5
	s_nop 0
	s_mov_b32 s5, m0
	s_mov_b32 m0, s72
	s_nop 0
	global_load_lds_dwordx4 v250, s[62:63]
	s_mov_b32 m0, s5
	s_nop 0
	s_mov_b32 s5, m0
	s_mov_b32 m0, s81
	s_nop 0
	global_load_lds_dwordx4 v247, s[62:63]
	s_mov_b32 m0, s5
	s_waitcnt vmcnt(8)
	s_waitcnt lgkmcnt(0)
	s_barrier
; #define PG8_STAGE(bufoff, gbase, voff) do { _Pragma("unroll") for (int _i = 0; _i < 2; ++_i) glds16_s((gbase), (voff)[_i], ldsb + (unsigned)((bufoff) + _i * 8192)); } while (0)
; #define PG8_LDA(dst, b, h) do { _Pragma("unroll") for (int m = 0; m < 4; ++m) _Pragma("unroll") for (int k = 0; k < 2; ++k) dst[m][k] = *(const LAS h16x8*)(lds + PG8_SA(b, h) + aoff + m * 2048 + k * 1024); } while (0)
; #define PG8_LDB(dst, b, h) do { _Pragma("unroll") for (int n = 0; n < 2; ++n) _Pragma("unroll") for (int k = 0; k < 2; ++k) dst[n][k] = *(const LAS h16x8*)(lds + PG8_SB(b, h) + boff + n * 2048 + k * 1024); } while (0)
; #define PG8_MMA(ai, bj, At, Bt) do { __builtin_amdgcn_s_setprio(1); _Pragma("unroll") for (int m = 0; m < 4; ++m) _Pragma("unroll") for (int n = 0; n < 2; ++n) _Pragma("unroll") for (int k = 0; k < 2; ++k) \
;         acc[ai][bj][m][n] = mma_step<I8>(Bt[n][k], At[m][k], acc[ai][bj][m][n]); __builtin_amdgcn_s_setprio(0); } while (0)
; #define PG8_WAIT_V(n) asm volatile("s_waitcnt vmcnt(" #n ")" ::: "memory")
; #define PG8_WAIT_L(n) asm volatile("s_waitcnt lgkmcnt(" #n ")" ::: "memory")
; #define PG8_BAR __builtin_amdgcn_s_barrier()
; #define PG8_SCHED __builtin_amdgcn_sched_barrier(0)
; template <class Prob, class Epi, bool I8 = false, bool ALIGN_EPI = true, bool SP2 = true>
; __device__ __forceinline__ void gemm_phase(LAS unsigned char* lds, int wave, const Prob& P, const Epi& E) {
;     ...
;             PG8_WAIT_V(8); PG8_WAIT_L(0); PG8_BAR; PG8_MMA(0, 0, At, B0); PG8_MMA(0, 1, At, B1); PG8_BAR; PG8_SCHED;
;             PG8_LDA(At, 0, 1); PG8_STAGE(PG8_SB(0, 0), b2, voffB); PG8_STAGE(PG8_SB(0, 1), b2 + hstepB, voffB); PG8_STAGE(PG8_SA(0, 0), a2, voffA);
;             PG8_WAIT_V(8); PG8_WAIT_L(0); PG8_BAR; PG8_MMA(1, 0, At, B0); PG8_MMA(1, 1, At, B1); PG8_BAR; PG8_SCHED;
;             PG8_LDB(B0, 1, 0); PG8_LDB(B1, 1, 1); PG8_SCHED; PG8_LDA(At, 1, 0); PG8_STAGE(PG8_SA(0, 1), a2 + hstepA, voffA);
;             PG8_WAIT_V(8); PG8_WAIT_L(0); PG8_BAR; PG8_MMA(0, 0, At, B0); PG8_MMA(0, 1, At, B1); PG8_BAR; PG8_SCHED;
	s_setprio 1
	s_waitcnt lgkmcnt(7)
	v_mfma_i32_16x16x64_i8 v[40:43], v[104:107], v[144:147], v[40:43]
	v_mfma_i32_16x16x64_i8 v[64:67], v[120:123], v[144:147], v[64:67]
	s_waitcnt lgkmcnt(5)
	v_mfma_i32_16x16x64_i8 v[36:39], v[104:107], v[168:171], v[36:39]
	v_mfma_i32_16x16x64_i8 v[60:63], v[120:123], v[168:171], v[60:63]
	s_waitcnt lgkmcnt(3)
	v_mfma_i32_16x16x64_i8 v[32:35], v[104:107], v[176:179], v[32:35]
	v_mfma_i32_16x16x64_i8 v[56:59], v[120:123], v[176:179], v[56:59]
	s_waitcnt lgkmcnt(1)
	v_mfma_i32_16x16x64_i8 v[104:107], v[104:107], v[184:187], v[156:159]
	v_mfma_i32_16x16x64_i8 v[40:43], v[112:115], v[164:167], v[40:43]
	v_mfma_i32_16x16x64_i8 v[64:67], v[124:127], v[164:167], v[64:67]
	v_mfma_i32_16x16x64_i8 v[36:39], v[112:115], v[172:175], v[36:39]
	v_mfma_i32_16x16x64_i8 v[60:63], v[124:127], v[172:175], v[60:63]
	v_mfma_i32_16x16x64_i8 v[32:35], v[112:115], v[180:183], v[32:35]
	v_mfma_i32_16x16x64_i8 v[56:59], v[124:127], v[180:183], v[56:59]
	s_waitcnt lgkmcnt(0)
	v_mfma_i32_16x16x64_i8 v[104:107], v[112:115], v[188:191], v[104:107]
	v_mfma_i32_16x16x64_i8 v[112:115], v[120:123], v[184:187], v[148:151]
	v_mfma_i32_16x16x64_i8 v[112:115], v[124:127], v[188:191], v[112:115]
	s_setprio 0
	s_setprio 1
	v_mfma_i32_16x16x64_i8 v[88:91], v[128:131], v[144:147], v[88:91]
	v_mfma_i32_16x16x64_i8 v[12:15], v[136:139], v[144:147], v[12:15]
	v_mfma_i32_16x16x64_i8 v[84:87], v[128:131], v[168:171], v[84:87]
	v_mfma_i32_16x16x64_i8 v[8:11], v[136:139], v[168:171], v[8:11]
	v_mfma_i32_16x16x64_i8 v[76:79], v[128:131], v[176:179], v[76:79]
	v_mfma_i32_16x16x64_i8 v[4:7], v[136:139], v[176:179], v[4:7]
	v_mfma_i32_16x16x64_i8 v[108:111], v[128:131], v[184:187], v[108:111]
	v_mfma_i32_16x16x64_i8 v[0:3], v[136:139], v[184:187], v[0:3]
	v_mfma_i32_16x16x64_i8 v[88:91], v[132:135], v[164:167], v[88:91]
	v_mfma_i32_16x16x64_i8 v[12:15], v[140:143], v[164:167], v[12:15]
	v_mfma_i32_16x16x64_i8 v[84:87], v[132:135], v[172:175], v[84:87]
	v_mfma_i32_16x16x64_i8 v[8:11], v[140:143], v[172:175], v[8:11]
	v_mfma_i32_16x16x64_i8 v[76:79], v[132:135], v[180:183], v[76:79]
	v_mfma_i32_16x16x64_i8 v[4:7], v[140:143], v[180:183], v[4:7]
	v_mfma_i32_16x16x64_i8 v[108:111], v[132:135], v[188:191], v[108:111]
	v_mfma_i32_16x16x64_i8 v[0:3], v[140:143], v[188:191], v[0:3]
	s_setprio 0
	s_barrier
	v_add_u32_e32 v132, 0x18000, v210
	v_add_u32_e32 v148, 0x1c000, v210
	ds_read_b128 v[120:123], v132
	ds_read_b128 v[124:127], v132 offset:1024
	ds_read_b128 v[128:131], v132 offset:2048
	ds_read_b128 v[132:135], v132 offset:3072
	ds_read_b128 v[136:139], v148
	ds_read_b128 v[140:143], v148 offset:1024
	ds_read_b128 v[144:147], v148 offset:2048
	ds_read_b128 v[164:167], v148 offset:3072
	ds_read_b128 v[148:151], v211 offset:32768
	ds_read_b128 v[156:159], v211 offset:33792
	ds_read_b128 v[168:171], v211 offset:34816
	ds_read_b128 v[172:175], v211 offset:35840
	ds_read_b128 v[176:179], v211 offset:36864
	ds_read_b128 v[180:183], v211 offset:37888
	ds_read_b128 v[184:187], v211 offset:38912
	ds_read_b128 v[188:191], v211 offset:39936
	s_add_u32 s6, s62, 0x2000
	s_addc_u32 s7, s63, 0
	s_mov_b32 s5, m0
	s_mov_b32 m0, s82
	s_nop 0
	global_load_lds_dwordx4 v250, s[6:7]
	s_mov_b32 m0, s5
	s_nop 0
	s_mov_b32 s5, m0
	s_mov_b32 m0, s83
	s_nop 0
	global_load_lds_dwordx4 v247, s[6:7]
	s_mov_b32 m0, s5
	s_waitcnt vmcnt(8)
	s_waitcnt lgkmcnt(0)
	s_barrier
	s_setprio 1
	s_waitcnt lgkmcnt(7)
	v_mfma_i32_16x16x64_i8 v[160:163], v[120:123], v[148:151], v[160:163]
	v_mfma_i32_16x16x64_i8 v[152:155], v[128:131], v[148:151], v[152:155]
	s_waitcnt lgkmcnt(5)
	v_mfma_i32_16x16x64_i8 v[52:55], v[120:123], v[168:171], v[52:55]
	v_mfma_i32_16x16x64_i8 v[80:83], v[128:131], v[168:171], v[80:83]
	s_waitcnt lgkmcnt(3)
	v_mfma_i32_16x16x64_i8 v[48:51], v[120:123], v[176:179], v[48:51]
	v_mfma_i32_16x16x64_i8 v[72:75], v[128:131], v[176:179], v[72:75]
	s_waitcnt lgkmcnt(1)
	v_mfma_i32_16x16x64_i8 v[44:47], v[120:123], v[184:187], v[44:47]
	v_mfma_i32_16x16x64_i8 v[68:71], v[128:131], v[184:187], v[68:71]
	v_mfma_i32_16x16x64_i8 v[160:163], v[124:127], v[156:159], v[160:163]
	v_mfma_i32_16x16x64_i8 v[152:155], v[132:135], v[156:159], v[152:155]
	v_mfma_i32_16x16x64_i8 v[52:55], v[124:127], v[172:175], v[52:55]
	v_mfma_i32_16x16x64_i8 v[80:83], v[132:135], v[172:175], v[80:83]
	v_mfma_i32_16x16x64_i8 v[48:51], v[124:127], v[180:183], v[48:51]
	v_mfma_i32_16x16x64_i8 v[72:75], v[132:135], v[180:183], v[72:75]
	s_waitcnt lgkmcnt(0)
	v_mfma_i32_16x16x64_i8 v[44:47], v[124:127], v[188:191], v[44:47]
	v_mfma_i32_16x16x64_i8 v[68:71], v[132:135], v[188:191], v[68:71]
	s_setprio 0
	s_setprio 1
	v_mfma_i32_16x16x64_i8 v[116:119], v[136:139], v[148:151], v[116:119]
	v_mfma_i32_16x16x64_i8 v[28:31], v[144:147], v[148:151], v[28:31]
	v_mfma_i32_16x16x64_i8 v[100:103], v[136:139], v[168:171], v[100:103]
	v_mfma_i32_16x16x64_i8 v[24:27], v[144:147], v[168:171], v[24:27]
	v_mfma_i32_16x16x64_i8 v[96:99], v[136:139], v[176:179], v[96:99]
	v_mfma_i32_16x16x64_i8 v[20:23], v[144:147], v[176:179], v[20:23]
	v_mfma_i32_16x16x64_i8 v[92:95], v[136:139], v[184:187], v[92:95]
	v_mfma_i32_16x16x64_i8 v[16:19], v[144:147], v[184:187], v[16:19]
	v_mfma_i32_16x16x64_i8 v[116:119], v[140:143], v[156:159], v[116:119]
	v_mfma_i32_16x16x64_i8 v[28:31], v[164:167], v[156:159], v[28:31]
	v_mfma_i32_16x16x64_i8 v[100:103], v[140:143], v[172:175], v[100:103]
	v_mfma_i32_16x16x64_i8 v[24:27], v[164:167], v[172:175], v[24:27]
	v_mfma_i32_16x16x64_i8 v[96:99], v[140:143], v[180:183], v[96:99]
	v_mfma_i32_16x16x64_i8 v[20:23], v[164:167], v[180:183], v[20:23]
	v_mfma_i32_16x16x64_i8 v[92:95], v[140:143], v[188:191], v[92:95]
	v_mfma_i32_16x16x64_i8 v[16:19], v[164:167], v[188:191], v[16:19]
	s_setprio 0
	s_barrier
; #define PG8_STAGE(bufoff, gbase, voff) do { _Pragma("unroll") for (int _i = 0; _i < 2; ++_i) glds16_s((gbase), (voff)[_i], ldsb + (unsigned)((bufoff) + _i * 8192)); } while (0)
; #define PG8_LDA(dst, b, h) do { _Pragma("unroll") for (int m = 0; m < 4; ++m) _Pragma("unroll") for (int k = 0; k < 2; ++k) dst[m][k] = *(const LAS h16x8*)(lds + PG8_SA(b, h) + aoff + m * 2048 + k * 1024); } while (0)
; #define PG8_MMA(ai, bj, At, Bt) do { __builtin_amdgcn_s_setprio(1); _Pragma("unroll") for (int m = 0; m < 4; ++m) _Pragma("unroll") for (int n = 0; n < 2; ++n) _Pragma("unroll") for (int k = 0; k < 2; ++k) \
;         acc[ai][bj][m][n] = mma_step<I8>(Bt[n][k], At[m][k], acc[ai][bj][m][n]); __builtin_amdgcn_s_setprio(0); } while (0)
; #define PG8_WAIT_V(n) asm volatile("s_waitcnt vmcnt(" #n ")" ::: "memory")
; #define PG8_WAIT_L(n) asm volatile("s_waitcnt lgkmcnt(" #n ")" ::: "memory")
; #define PG8_BAR __builtin_amdgcn_s_barrier()
; #define PG8_SCHED __builtin_amdgcn_sched_barrier(0)
; template <class Prob, class Epi, bool I8 = false, bool ALIGN_EPI = true, bool SP2 = true>
; __device__ __forceinline__ void gemm_phase(LAS unsigned char* lds, int wave, const Prob& P, const Epi& E) {
;     ...
;             PG8_LDA(At, 1, 1); PG8_STAGE(PG8_SB(1, 0), b3, voffB); PG8_STAGE(PG8_SB(1, 1), b3 + hstepB, voffB); PG8_STAGE(PG8_SA(1, 0), a3, voffA);
;             PG8_WAIT_V(8); PG8_WAIT_L(0); PG8_BAR; PG8_MMA(1, 0, At, B0); PG8_MMA(1, 1, At, B1); PG8_BAR; PG8_SCHED;
;     ...
;         if constexpr (ALIGN_EPI) { if (wr == 0) PG8_BAR; }
	ds_read_b128 v[168:171], v211 offset:49152
	ds_read_b128 v[172:175], v211 offset:50176
	ds_read_b128 v[176:179], v211 offset:51200
	ds_read_b128 v[180:183], v211 offset:52224
	ds_read_b128 v[184:187], v211 offset:53248
	ds_read_b128 v[188:191], v211 offset:54272
	ds_read_b128 v[192:195], v211 offset:55296
	ds_read_b128 v[196:199], v211 offset:56320
	s_add_u32 s6, s68, 0x80
	s_addc_u32 s7, s69, 0
	s_mov_b32 s5, m0
	s_mov_b32 m0, s2
	s_nop 0
	global_load_lds_dwordx4 v217, s[6:7]
	s_mov_b32 m0, s5
	s_nop 0
	s_mov_b32 s5, m0
	s_mov_b32 m0, s85
	s_nop 0
	global_load_lds_dwordx4 v248, s[6:7]
	s_mov_b32 m0, s5
	s_add_u32 s6, s68, 0x40080
	s_addc_u32 s7, s69, 0
	s_mov_b32 s5, m0
	s_mov_b32 m0, s88
	s_nop 0
	global_load_lds_dwordx4 v217, s[6:7]
	s_mov_b32 m0, s5
	s_nop 0
	s_mov_b32 s5, m0
	s_mov_b32 m0, s89
	s_nop 0
	global_load_lds_dwordx4 v248, s[6:7]
	s_mov_b32 m0, s5
	s_nop 0
	s_mov_b32 s5, m0
	s_mov_b32 m0, s86
	s_nop 0
	global_load_lds_dwordx4 v250, s[60:61]
	s_mov_b32 m0, s5
	s_nop 0
	s_mov_b32 s5, m0
	s_mov_b32 m0, s87
	s_nop 0
	global_load_lds_dwordx4 v247, s[60:61]
	s_mov_b32 m0, s5
	s_waitcnt vmcnt(8)
	s_waitcnt lgkmcnt(0)
	s_barrier
	s_setprio 1
	s_waitcnt lgkmcnt(1)
	v_mfma_i32_16x16x64_i8 v[104:107], v[120:123], v[192:195], v[104:107]
	v_mfma_i32_16x16x64_i8 v[40:43], v[120:123], v[168:171], v[40:43]
	v_mfma_i32_16x16x64_i8 v[64:67], v[128:131], v[168:171], v[64:67]
	v_mfma_i32_16x16x64_i8 v[36:39], v[120:123], v[176:179], v[36:39]
	v_mfma_i32_16x16x64_i8 v[60:63], v[128:131], v[176:179], v[60:63]
	v_mfma_i32_16x16x64_i8 v[32:35], v[120:123], v[184:187], v[32:35]
	v_mfma_i32_16x16x64_i8 v[56:59], v[128:131], v[184:187], v[56:59]
	s_waitcnt lgkmcnt(0)
	v_mfma_i32_16x16x64_i8 v[156:159], v[124:127], v[196:199], v[104:107]
	v_mfma_i32_16x16x64_i8 v[104:107], v[128:131], v[192:195], v[112:115]
	v_mfma_i32_16x16x64_i8 v[40:43], v[124:127], v[172:175], v[40:43]
	v_mfma_i32_16x16x64_i8 v[64:67], v[132:135], v[172:175], v[64:67]
	v_mfma_i32_16x16x64_i8 v[36:39], v[124:127], v[180:183], v[36:39]
	v_mfma_i32_16x16x64_i8 v[60:63], v[132:135], v[180:183], v[60:63]
	v_mfma_i32_16x16x64_i8 v[32:35], v[124:127], v[188:191], v[32:35]
	v_mfma_i32_16x16x64_i8 v[56:59], v[132:135], v[188:191], v[56:59]
	v_mfma_i32_16x16x64_i8 v[148:151], v[132:135], v[196:199], v[104:107]
	s_setprio 0
	s_setprio 1
	v_mfma_i32_16x16x64_i8 v[88:91], v[136:139], v[168:171], v[88:91]
	v_mfma_i32_16x16x64_i8 v[12:15], v[144:147], v[168:171], v[12:15]
	v_mfma_i32_16x16x64_i8 v[84:87], v[136:139], v[176:179], v[84:87]
	v_mfma_i32_16x16x64_i8 v[8:11], v[144:147], v[176:179], v[8:11]
	v_mfma_i32_16x16x64_i8 v[76:79], v[136:139], v[184:187], v[76:79]
	v_mfma_i32_16x16x64_i8 v[4:7], v[144:147], v[184:187], v[4:7]
	v_mfma_i32_16x16x64_i8 v[104:107], v[136:139], v[192:195], v[108:111]
	v_mfma_i32_16x16x64_i8 v[0:3], v[144:147], v[192:195], v[0:3]
	v_mfma_i32_16x16x64_i8 v[88:91], v[140:143], v[172:175], v[88:91]
	v_mfma_i32_16x16x64_i8 v[12:15], v[164:167], v[172:175], v[12:15]
	v_mfma_i32_16x16x64_i8 v[84:87], v[140:143], v[180:183], v[84:87]
	v_mfma_i32_16x16x64_i8 v[8:11], v[164:167], v[180:183], v[8:11]
	v_mfma_i32_16x16x64_i8 v[76:79], v[140:143], v[188:191], v[76:79]
	v_mfma_i32_16x16x64_i8 v[4:7], v[164:167], v[188:191], v[4:7]
	v_mfma_i32_16x16x64_i8 v[108:111], v[140:143], v[196:199], v[104:107]
	v_mfma_i32_16x16x64_i8 v[0:3], v[164:167], v[196:199], v[0:3]
	s_setprio 0
	s_barrier
	s_add_i32 s4, s4, 2
	s_add_u32 vcc_lo, vcc_lo, 0x100
	s_addc_u32 vcc_hi, vcc_hi, 0
	s_add_u32 s0, s0, 0x100
	s_addc_u32 s1, s1, 0
	s_add_u32 s44, s44, 0x100
	s_addc_u32 s45, s45, 0
	s_cmp_gt_u32 s4, 13
	s_cbranch_scc0 .LBB0_1065
	s_mov_b32 s100, 0xbfb8aa3b
	s_mov_b32 s101, 0

; #define PG8_BAR __builtin_amdgcn_s_barrier()
;     __device__ bool next(int i, Unit& u) const { return S.next(i, u); }
; template <class Prob, class Epi, bool I8 = false, bool ALIGN_EPI = true, bool SP2 = true>
; __device__ __forceinline__ void gemm_phase(LAS unsigned char* lds, int wave, const Prob& P, const Epi& E) {
;     ...
;         if constexpr (ALIGN_EPI) { if (wr == 0) PG8_BAR; }
;     __device__ __forceinline__ void operator()(Acc& acc, const Unit& u, int wr, int wc, int fr, int fq, LAS unsigned char* lds, int tid) const {
;     ...
;         if constexpr (I8) {
; #pragma unroll
;             for (int ai = 0; ai < 2; ++ai) { const f32x4 sa = ldf4(sx, tok0 + tl0 + 4u * ai);
; #pragma unroll
;                 for (int m = 0; m < 4; ++m)
; #pragma unroll
;                     for (int bj = 0; bj < 2; ++bj)
; #pragma unroll
;                         for (int n = 0; n < 2; ++n) { const pg8::i32x4 iv = __builtin_bit_cast(pg8::i32x4, acc[ai][bj][m][n]); acc[ai][bj][m][n] = __builtin_convertvector(iv, f32x4) * sa[m]; }
;                 asm volatile("" ::: "memory"); }
;         }
;         const unsigned bk = 2 * u.pm + wr;
;         const bool lvalid = (bk & 15) != 0, rvalid = (bk & 15) != 15;
; #pragma unroll
;         for (int bj = 0; bj < 2; ++bj) {
;             const unsigned colp = u.pn * 256 + bj * 128 + wc * 32 + 8 * fq;
;             const unsigned coll = bj * FF + u.pn * 128 + wc * 32 + 8 * fq;
; #pragma unroll
;             for (int n = 0; n < 2; ++n) {
;                 f32x4 c0 = ldf4(cw, coll + 4u * n), c1 = ldf4(cw, (unsigned)FF2 + coll + 4u * n), c2 = ldf4(cw, 2u * FF2 + coll + 4u * n);
;                 if constexpr (I8) { const f32x4 swv = ldf4(sw, colp + 4u * n); c0 = c0 * swv; c1 = c1 * swv; c2 = c2 * swv; }
;                 f32x4 hl = {0.f, 0.f, 0.f, 0.f}, hr = {0.f, 0.f, 0.f, 0.f};
;                 if (fr == 0 && lvalid) hl = ldf4(HALO, (2u * bk) * (unsigned)FF2 + colp + 4u * n);
;                 if (fr == 15 && rvalid) hr = ldf4(HALO, (2u * bk + 1u) * (unsigned)FF2 + colp + 4u * n);
; #pragma unroll
;                 for (int e = 0; e < 4; ++e) {
;                     const float prev = dpp_shr1(hl[e], acc[1][bj][3][n][e]);
;                     const float next = dpp_shl1(hr[e], acc[0][bj][0][n][e]);
.Lzs_5e:
	s_and_saveexec_b64 s[60:61], vcc
	global_load_dwordx4 v[204:207], v183, s[38:39]
	s_or_b64 exec, exec, s[60:61]
	v_mov_b32_e32 v147, v209
	v_lshl_add_u64 v[180:181], s[28:29], 0, v[146:147]
	v_cvt_f32_i32_e32 v147, v161
	v_cvt_f32_i32_e32 v146, v160
	v_cvt_f32_i32_e32 v161, v163
	v_cvt_f32_i32_e32 v160, v162
	v_lshl_add_u64 v[164:165], s[22:23], 0, v[208:209]
	v_cvt_f32_i32_e32 v149, v149
	v_cvt_f32_i32_e32 v148, v148
	v_cvt_f32_i32_e32 v153, v153
	v_cvt_f32_i32_e32 v152, v152
	v_cvt_f32_i32_e32 v155, v155
	v_cvt_f32_i32_e32 v154, v154
	v_cvt_f32_i32_e32 v151, v151
	v_cvt_f32_i32_e32 v150, v150
	v_cvt_f32_i32_e32 v117, v117
	v_cvt_f32_i32_e32 v116, v116
	v_cvt_f32_i32_e32 v109, v109
	v_cvt_f32_i32_e32 v108, v108
	v_cvt_f32_i32_e32 v119, v119
	v_cvt_f32_i32_e32 v118, v118
	v_cvt_f32_i32_e32 v111, v111
	v_cvt_f32_i32_e32 v110, v110
	v_cvt_f32_i32_e32 v53, v53
	v_cvt_f32_i32_e32 v52, v52
	v_cvt_f32_i32_e32 v49, v49
	v_cvt_f32_i32_e32 v48, v48
	v_cvt_f32_i32_e32 v45, v45
	v_cvt_f32_i32_e32 v44, v44
	v_cvt_f32_i32_e32 v41, v41
	v_cvt_f32_i32_e32 v40, v40
	v_cvt_f32_i32_e32 v37, v37
	v_cvt_f32_i32_e32 v36, v36
	v_cvt_f32_i32_e32 v33, v33
	v_cvt_f32_i32_e32 v32, v32
	v_cvt_f32_i32_e32 v55, v55
	v_cvt_f32_i32_e32 v54, v54
	v_cvt_f32_i32_e32 v51, v51
	v_cvt_f32_i32_e32 v50, v50
	v_cvt_f32_i32_e32 v47, v47
	v_cvt_f32_i32_e32 v46, v46
	v_cvt_f32_i32_e32 v43, v43
	v_cvt_f32_i32_e32 v42, v42
	v_cvt_f32_i32_e32 v39, v39
	v_cvt_f32_i32_e32 v38, v38
	v_cvt_f32_i32_e32 v27, v27
	v_cvt_f32_i32_e32 v26, v26
	v_cvt_f32_i32_e32 v13, v13
	v_cvt_f32_i32_e32 v12, v12
	v_cvt_f32_i32_e32 v35, v35
	v_cvt_f32_i32_e32 v34, v34
	v_cvt_f32_i32_e32 v101, v101
	v_cvt_f32_i32_e32 v100, v100
	v_cvt_f32_i32_e32 v97, v97
	v_cvt_f32_i32_e32 v96, v96
	v_cvt_f32_i32_e32 v93, v93
	v_cvt_f32_i32_e32 v92, v92
	v_cvt_f32_i32_e32 v11, v11
	v_cvt_f32_i32_e32 v10, v10
	v_cvt_f32_i32_e32 v89, v89
	v_cvt_f32_i32_e32 v88, v88
	v_cvt_f32_i32_e32 v31, v31
	v_cvt_f32_i32_e32 v30, v30
	v_cvt_f32_i32_e32 v17, v17
	v_cvt_f32_i32_e32 v16, v16
	v_cvt_f32_i32_e32 v85, v85
	v_cvt_f32_i32_e32 v84, v84
	v_cvt_f32_i32_e32 v77, v77
	v_cvt_f32_i32_e32 v79, v79
	v_cvt_f32_i32_e32 v78, v78
	v_cvt_f32_i32_e32 v76, v76
	v_cvt_f32_i32_e32 v57, v57
	v_cvt_f32_i32_e32 v59, v59
	v_cvt_f32_i32_e32 v58, v58
	v_cvt_f32_i32_e32 v56, v56
	v_cvt_f32_i32_e32 v7, v7
	v_cvt_f32_i32_e32 v6, v6
	v_cvt_f32_i32_e32 v103, v103
	v_cvt_f32_i32_e32 v102, v102
	v_cvt_f32_i32_e32 v99, v99
	v_cvt_f32_i32_e32 v98, v98
	v_cvt_f32_i32_e32 v95, v95
	v_cvt_f32_i32_e32 v94, v94
	v_cvt_f32_i32_e32 v91, v91
	v_cvt_f32_i32_e32 v90, v90
	v_cvt_f32_i32_e32 v87, v87
	v_cvt_f32_i32_e32 v86, v86
	v_cvt_f32_i32_e32 v81, v81
	v_cvt_f32_i32_e32 v80, v80
	v_cvt_f32_i32_e32 v73, v73
	v_cvt_f32_i32_e32 v72, v72
	v_cvt_f32_i32_e32 v69, v69
	v_cvt_f32_i32_e32 v68, v68
	v_cvt_f32_i32_e32 v65, v65
	v_cvt_f32_i32_e32 v64, v64
	v_cvt_f32_i32_e32 v61, v61
	v_cvt_f32_i32_e32 v60, v60
	v_cvt_f32_i32_e32 v83, v83
	v_cvt_f32_i32_e32 v82, v82
	v_cvt_f32_i32_e32 v67, v67
	v_cvt_f32_i32_e32 v66, v66
	v_cvt_f32_i32_e32 v63, v63
	v_cvt_f32_i32_e32 v62, v62
	v_cvt_f32_i32_e32 v29, v29
	v_cvt_f32_i32_e32 v28, v28
	v_cvt_f32_i32_e32 v25, v25
	v_cvt_f32_i32_e32 v24, v24
	v_cvt_f32_i32_e32 v19, v19
	v_cvt_f32_i32_e32 v18, v18
	v_cvt_f32_i32_e32 v15, v15
	v_cvt_f32_i32_e32 v14, v14
	v_cvt_f32_i32_e32 v75, v75
	v_cvt_f32_i32_e32 v74, v74
	v_cvt_f32_i32_e32 v23, v23
	v_cvt_f32_i32_e32 v22, v22
	v_cvt_f32_i32_e32 v21, v21
	v_cvt_f32_i32_e32 v20, v20
	v_cvt_f32_i32_e32 v71, v71
	v_cvt_f32_i32_e32 v70, v70
	s_cmp_eq_u64 s[46:47], 0
	s_cbranch_scc1 .Lalign_1068
	s_barrier
.Lalign_1068:
	s_waitcnt vmcnt(7)
	v_pk_mul_f32 v[224:225], v[112:113], v[146:147] op_sel_hi:[0,1]
	v_cvt_f32_i32_e32 v147, v157
	v_cvt_f32_i32_e32 v146, v156
	v_cvt_f32_i32_e32 v157, v159
	v_cvt_f32_i32_e32 v156, v158
	s_waitcnt vmcnt(6)
	v_mov_b32_e32 v158, v107
	v_add_u32_e32 v145, 0xb010, v208
	v_pk_mul_f32 v[220:221], v[112:113], v[160:161] op_sel_hi:[0,1]
	v_pk_mul_f32 v[218:219], v[158:159], v[156:157] op_sel_hi:[0,1]
	v_pk_mul_f32 v[222:223], v[158:159], v[146:147] op_sel_hi:[0,1]
	global_load_dwordx4 v[160:163], v[164:165], off offset:16
	global_load_dwordx4 v[156:159], v145, s[22:23]
	v_add_u32_e32 v145, 0x16010, v208
	global_load_dwordx4 v[164:167], v145, s[22:23]
	global_load_dwordx4 v[168:171], v[180:181], off offset:16
	s_waitcnt vmcnt(6)
	v_mov_b32_dpp v120, v222 row_shr:1 row_mask:0xf bank_mask:0xf
	v_mov_b32_dpp v124, v224 row_shl:1 row_mask:0xf bank_mask:0xf
	v_mov_b32_dpp v121, v223 row_shr:1 row_mask:0xf bank_mask:0xf
	v_mov_b32_dpp v125, v225 row_shl:1 row_mask:0xf bank_mask:0xf
	v_mov_b32_dpp v122, v218 row_shr:1 row_mask:0xf bank_mask:0xf
	v_mov_b32_dpp v126, v220 row_shl:1 row_mask:0xf bank_mask:0xf
	v_mov_b32_dpp v123, v219 row_shr:1 row_mask:0xf bank_mask:0xf
	v_mov_b32_dpp v127, v221 row_shl:1 row_mask:0xf bank_mask:0xf
	s_cmp_lg_u64 s[44:45], 0
	s_cbranch_scc1 .Lzs_2
	v_mov_b32_e32 v145, 0
	v_mov_b32_e32 v146, 0
	v_mov_b32_e32 v147, 0
